# scan S1: C*B^T tile handled with a class-uniform mapping (row per 4 lanes, chunk = lane&3 + 4j): fully masked wave-blocks skipped (sCBL zeroed once per item), unmasked ones skip the causal select
# speedup vs baseline: 1.0095x; 1.0095x over previous
; DI void ssd_scan_phase(bf16_t* P, const bf16_t* BT, const bf16_t* Cc, const bf16_t* CB, const float* dt, const float* acs,
;                        const float* cw, const float* cb, const float* Dp, char* lds, bool dry, int mode, float* Sbuf) {
;     ...
;       const size_t cbis = cbi0 + (size_t)c0 * 65536;
;       const bf16_t* Cq = Cc + cbis; const bf16_t* Bq = BT + cbis; const bf16_t* CBq = CB + cbis;
; #pragma unroll
;       for (int j = 0; j < 4; ++j) { rB[j] = *(const u32x4*)(Bq + toff + j * 4096); rC[j] = (u32x4){0u, 0u, 0u, 0u}; rCB[j] = (u32x4){0u, 0u, 0u, 0u};
;         if (mode == 0) { rC[j] = *(const u32x4*)(Cq + toff + j * 4096); rCB[j] = *(const u32x4*)(CBq + toff + j * 4096); } }
.LBB0_1027:
	s_or_b64 exec, exec, s[56:57]
	s_ashr_i32 s78, s68, 7
	s_lshl_b32 s80, s78, s37
	s_ashr_i32 s81, s80, 31
	s_lshl_b32 s56, s34, 22
	s_lshl_b32 s57, s69, 14
	s_or_b32 s76, s56, s57
	s_lshl_b64 s[56:57], s[80:81], 16
	s_add_u32 s56, s56, s76
	s_addc_u32 s57, s57, 0
	s_lshl_b64 s[70:71], s[56:57], 1
	v_lshl_add_u64 v[22:23], v[142:143], 0, s[70:71]
	global_load_dwordx4 v[60:63], v[22:23], off
	v_cndmask_b32_e64 v0, 0, 1, s[60:61]
	s_mov_b32 s77, s35
	v_lshl_add_u64 v[20:21], v[144:145], 0, s[70:71]
	v_cmp_ne_u32_e64 s[56:57], 1, v0
	s_andn2_b64 vcc, exec, s[60:61]
	v_lshl_add_u64 v[24:25], v[146:147], 0, s[70:71]
	s_cbranch_vccnz .LBB0_1029
	global_load_dwordx4 v[52:55], v[24:25], off
	v_lshrrev_b32_e32 v26, 4, v200
	v_and_b32_e32 v27, 15, v200
	v_lshlrev_b32_e32 v27, 4, v27
	v_lshl_or_b32 v26, v26, 8, v27
	v_sub_co_u32_e32 v26, vcc, v20, v26
	s_nop 1
	v_subbrev_co_u32_e32 v27, vcc, 0, v21, vcc
	v_lshrrev_b32_e32 v28, 2, v200
	v_sub_u32_e32 v28, 0x7f, v28
	v_and_b32_e32 v29, 3, v200
	v_lshlrev_b32_e32 v29, 4, v29
	v_lshl_or_b32 v28, v28, 8, v29
	v_add_co_u32_e32 v26, vcc, v26, v28
	s_nop 1
	v_addc_co_u32_e32 v27, vcc, 0, v27, vcc
	global_load_dwordx4 v[56:59], v[26:27], off
	s_branch .LBB0_1030

; DI void ssd_scan_phase(bf16_t* P, const bf16_t* BT, const bf16_t* Cc, const bf16_t* CB, const float* dt, const float* acs,
;                        const float* cw, const float* cb, const float* Dp, char* lds, bool dry, int mode, float* Sbuf) {
;     ...
; #pragma unroll
;       for (int j = 0; j < 4; ++j) { rB[j] = *(const u32x4*)(Bq + toff + j * 4096); rC[j] = (u32x4){0u, 0u, 0u, 0u}; rCB[j] = (u32x4){0u, 0u, 0u, 0u};
;         if (mode == 0) { rC[j] = *(const u32x4*)(Cq + toff + j * 4096); rCB[j] = *(const u32x4*)(CBq + toff + j * 4096); } }
.LBB0_1030:
	s_waitcnt vmcnt(4)
	v_add_co_u32_e32 v2, vcc, 0x2000, v22
	s_nop 1
	v_addc_co_u32_e32 v3, vcc, 0, v23, vcc
	global_load_dwordx4 v[76:79], v[2:3], off
	s_and_b64 vcc, exec, s[56:57]
	s_cbranch_vccnz .LBB0_1032
	v_add_co_u32_e32 v2, vcc, 0x2000, v24
	s_nop 1
	v_addc_co_u32_e32 v3, vcc, 0, v25, vcc
	global_load_dwordx4 v[64:67], v[2:3], off
	global_load_dwordx4 v[68:71], v[26:27], off offset:64
	s_branch .LBB0_1033

; DI void ssd_scan_phase(bf16_t* P, const bf16_t* BT, const bf16_t* Cc, const bf16_t* CB, const float* dt, const float* acs,
;                        const float* cw, const float* cb, const float* Dp, char* lds, bool dry, int mode, float* Sbuf) {
;     ...
; #pragma unroll
;       for (int j = 0; j < 4; ++j) { rB[j] = *(const u32x4*)(Bq + toff + j * 4096); rC[j] = (u32x4){0u, 0u, 0u, 0u}; rCB[j] = (u32x4){0u, 0u, 0u, 0u};
;         if (mode == 0) { rC[j] = *(const u32x4*)(Cq + toff + j * 4096); rCB[j] = *(const u32x4*)(CBq + toff + j * 4096); } }
.LBB0_1033:
	v_add_co_u32_e32 v2, vcc, 0x4000, v22
	s_nop 1
	v_addc_co_u32_e32 v3, vcc, 0, v23, vcc
	global_load_dwordx4 v[92:95], v[2:3], off
	s_and_b64 vcc, exec, s[56:57]
	s_cbranch_vccnz .LBB0_1035
	v_add_co_u32_e32 v2, vcc, 0x4000, v24
	s_nop 1
	v_addc_co_u32_e32 v3, vcc, 0, v25, vcc
	global_load_dwordx4 v[72:75], v[2:3], off
	global_load_dwordx4 v[80:83], v[26:27], off offset:128
	s_branch .LBB0_1036

; DI void ssd_scan_phase(bf16_t* P, const bf16_t* BT, const bf16_t* Cc, const bf16_t* CB, const float* dt, const float* acs,
;                        const float* cw, const float* cb, const float* Dp, char* lds, bool dry, int mode, float* Sbuf) {
;     ...
; #pragma unroll
;       for (int j = 0; j < 4; ++j) { rB[j] = *(const u32x4*)(Bq + toff + j * 4096); rC[j] = (u32x4){0u, 0u, 0u, 0u}; rCB[j] = (u32x4){0u, 0u, 0u, 0u};
;         if (mode == 0) { rC[j] = *(const u32x4*)(Cq + toff + j * 4096); rCB[j] = *(const u32x4*)(CBq + toff + j * 4096); } }
.LBB0_1036:
	v_add_co_u32_e32 v2, vcc, 0x6000, v22
	s_nop 1
	v_addc_co_u32_e32 v3, vcc, 0, v23, vcc
	global_load_dwordx4 v[104:107], v[2:3], off
	s_and_b64 vcc, exec, s[56:57]
	s_cbranch_vccnz .LBB0_1038
	v_add_co_u32_e32 v2, vcc, 0x6000, v24
	s_nop 1
	v_addc_co_u32_e32 v3, vcc, 0, v25, vcc
	global_load_dwordx4 v[84:87], v[2:3], off
	global_load_dwordx4 v[88:91], v[26:27], off offset:192
	s_branch .LBB0_1039

; DI u32x4 pack8(const float (&f)[8]) { u32x4 r; r[0] = pk2(f[0], f[1]); r[1] = pk2(f[2], f[3]); r[2] = pk2(f[4], f[5]); r[3] = pk2(f[6], f[7]); return r; }
; DI void ssd_scan_phase(bf16_t* P, const bf16_t* BT, const bf16_t* Cc, const bf16_t* CB, const float* dt, const float* acs,
;                        const float* cw, const float* cb, const float* Dp, char* lds, bool dry, int mode, float* Sbuf) {
;     ...
;       if (tid < 128) { sAcs[tid] = aq[tid * 32]; sDt[tid] = dq[tid * 32]; racs = aq[4096 + tid * 32]; rdt = dq[4096 + tid * 32]; }
;     }
;     __syncthreads();
; #pragma unroll 1
;     for (int c = c0; c < c1; ++c) {
;       const size_t t0 = tb + c * 128;
;       const float* cAcs = sAcs + (c & 1) * 128; const float* cDt = sDt + (c & 1) * 128;
;       {
;         int xl = xl_, xc = xc_, r0 = r0_, cch = cch_;
;         asm volatile("" : "+v"(xl), "+v"(xc), "+v"(r0), "+v"(cch));
;         const f32x4 a0 = *(const f32x4*)(cAcs + cch * 8), a1 = *(const f32x4*)(cAcs + cch * 8 + 4);
;         const float L2E = 1.44269504f;
;         const float as[8] = {a0[0] * L2E, a0[1] * L2E, a0[2] * L2E, a0[3] * L2E, a1[0] * L2E, a1[1] * L2E, a1[2] * L2E, a1[3] * L2E};
; #pragma unroll
;         for (int j = 0; j < 4; ++j) {
;           const int r = r0 + 32 * j;
;           *(u32x4*)(sBT + swz128(r, cch)) = rB[j];
;           if (mode == 0) {
;             *(u32x4*)(sC + swz128(r, cch)) = rC[j];
;             float f[8]; unpack8(rCB[j], f);
;             const float el = cAcs[r] * L2E;
;             const int lim = r - cch * 8;
; #pragma unroll
;             for (int e = 0; e < 8; ++e) f[e] = (e <= lim) ? f[e] * __builtin_amdgcn_exp2f(el - as[e]) : 0.f;
;             *(u32x4*)(sCBL + swz128(r, cch)) = pack8(f);
.LBB0_1053:
	s_or_b64 exec, exec, s[78:79]
	v_readlane_b32 s4, v253, 16
	s_add_i32 s69, s80, s28
	v_readlane_b32 s18, v253, 30
	v_readlane_b32 s19, v253, 31
	s_add_u32 s72, s18, s34
	v_readlane_b32 s16, v253, 28
	s_addc_u32 s73, s19, 0
	s_mov_b32 s75, s35
	v_lshl_add_u64 v[20:21], v[124:125], 0, s[76:77]
	s_lshl_b64 s[76:77], s[80:81], 17
	v_readlane_b32 s17, v253, 29
	v_lshl_add_u64 v[164:165], v[150:151], 0, s[74:75]
	v_lshl_add_u64 v[166:167], v[152:153], 0, s[74:75]
	s_add_u32 s74, s16, s76
	s_addc_u32 s75, s17, s77
	s_add_u32 s76, s20, s76
	s_addc_u32 s77, s21, s77
	s_lshl_b32 s78, s80, 13
	s_add_i32 s85, s78, 0x2000
	s_lshl_b32 s78, s80, 7
	s_waitcnt vmcnt(0)
	v_mov_b32_e32 v157, v156
	v_lshlrev_b64 v[168:169], 1, v[20:21]
	v_mov_b32_e32 v170, s78
	v_lshlrev_b32_e32 v46, 4, v200
	v_mov_b32_e32 v36, 0
	v_mov_b32_e32 v37, 0
	v_mov_b32_e32 v38, 0
	v_mov_b32_e32 v39, 0
	ds_write_b128 v46, v[36:39]
	ds_write_b128 v46, v[36:39] offset:8192
	ds_write_b128 v46, v[36:39] offset:16384
	ds_write_b128 v46, v[36:39] offset:24576
	s_waitcnt lgkmcnt(0)
	s_barrier
	v_readlane_b32 s5, v253, 17
	v_readlane_b32 s6, v253, 18
	v_readlane_b32 s7, v253, 19
	v_readlane_b32 s8, v253, 20
	v_readlane_b32 s9, v253, 21
	v_readlane_b32 s10, v253, 22
	v_readlane_b32 s11, v253, 23
	v_readlane_b32 s12, v253, 24
	v_readlane_b32 s13, v253, 25
	v_readlane_b32 s14, v253, 26
	v_readlane_b32 s15, v253, 27
.LBB0_1054:
	s_and_b32 s90, s80, 1
	s_lshl_b32 s78, s90, 9
	s_add_i32 s88, s78, 0
	s_add_i32 s88, s88, 0x22800
	v_mov_b32_e32 v34, v177
	v_mov_b32_e32 v40, v178
	v_mov_b32_e32 v29, v176
	v_mov_b32_e32 v41, v179
	s_cmp_lg_u64 s[56:57], 0
	s_cbranch_scc0 .Ls1n
	s_mov_b64 s[78:79], -1
	v_lshl_add_u32 v24, v34, 5, s88
	ds_read_b128 v[20:23], v24
	ds_read_b128 v[30:33], v24 offset:16
	v_lshl_add_u32 v47, v29, 2, s88
	ds_read_b32 v48, v47
	ds_read_b32 v49, v47 offset:128
	ds_read_b32 v50, v47 offset:256
	ds_read_b32 v51, v47 offset:384
	v_lshlrev_b32_e32 v26, 3, v34
	s_and_b64 vcc, exec, s[56:57]
	s_waitcnt lgkmcnt(5)
	v_mul_f32_e32 v24, 0x3fb8aa3b, v23
	s_waitcnt lgkmcnt(4)
	v_mul_f32_e32 v23, 0x3fb8aa3b, v30
	v_bitop3_b32 v30, v29, v34, 15 bitop3:0x6c
	v_mul_f32_e32 v27, 0x3fb8aa3b, v21
	v_mul_f32_e32 v21, 0x3fb8aa3b, v32
	v_lshlrev_b32_e32 v30, 4, v30
	v_lshlrev_b32_e32 v32, 8, v29
	v_mul_f32_e32 v25, 0x3fb8aa3b, v22
	v_mul_f32_e32 v22, 0x3fb8aa3b, v31
	v_add_u32_e32 v31, v30, v32
	v_mul_f32_e32 v28, 0x3fb8aa3b, v20
	v_mul_f32_e32 v20, 0x3fb8aa3b, v33
	v_add_u32_e32 v33, 0, v31
	v_add_u32_e32 v31, 0x10000, v33
	s_cmp_lg_u64 s[42:43], 0
	s_cbranch_scc1 .Lscan_w47_0
	s_waitcnt vmcnt(17)
	s_branch .Lscan_wdone_0

; DI void ssd_scan_phase(bf16_t* P, const bf16_t* BT, const bf16_t* Cc, const bf16_t* CB, const float* dt, const float* acs,
;                        const float* cw, const float* cb, const float* Dp, char* lds, bool dry, int mode, float* Sbuf) {
;     ...
;       if (c + 1 < c1) {
;         if (c + 2 < c1 && tid < 128) { nacs = (acs + (t0 + 256) * 32 + hh)[tid * 32]; ndt = (dt + (t0 + 256) * 32 + hh)[tid * 32]; }
;         const size_t cbi = cbi0 + (size_t)(c + 1) * 65536;
;         const bf16_t* Cq = Cc + cbi; const bf16_t* Bq = BT + cbi; const bf16_t* CBq = CB + cbi;
; #pragma unroll
;         for (int j = 0; j < 4; ++j) { rB[j] = *(const u32x4*)(Bq + toff + j * 4096); if (mode == 0) { rC[j] = *(const u32x4*)(Cq + toff + j * 4096); rCB[j] = *(const u32x4*)(CBq + toff + j * 4096); } }
.LBB0_1085:
	s_or_b64 exec, exec, s[80:81]
	v_lshl_add_u64 v[22:23], s[74:75], 0, v[168:169]
	v_add_co_u32_e32 v20, vcc, 0x20000, v22
	s_nop 1
	v_addc_co_u32_e32 v21, vcc, 0, v23, vcc
	global_load_dwordx4 v[60:63], v[20:21], off
	s_and_b64 vcc, exec, s[56:57]
	v_lshl_add_u64 v[20:21], s[76:77], 0, v[168:169]
	s_cbranch_vccnz .LBB0_1087
	v_add_co_u32_e32 v24, vcc, 0x1020000, v22
	s_nop 1
	v_addc_co_u32_e32 v25, vcc, 0, v23, vcc
	global_load_dwordx4 v[52:55], v[24:25], off
	v_lshrrev_b32_e32 v26, 4, v200
	v_and_b32_e32 v27, 15, v200
	v_lshlrev_b32_e32 v27, 4, v27
	v_lshl_or_b32 v26, v26, 8, v27
	v_sub_co_u32_e32 v26, vcc, v20, v26
	s_nop 1
	v_subbrev_co_u32_e32 v27, vcc, 0, v21, vcc
	v_lshrrev_b32_e32 v28, 2, v200
	v_sub_u32_e32 v28, 0x7f, v28
	v_and_b32_e32 v29, 3, v200
	v_lshlrev_b32_e32 v29, 4, v29
	v_lshl_or_b32 v28, v28, 8, v29
	v_add_co_u32_e32 v26, vcc, v26, v28
	s_nop 1
	v_addc_co_u32_e32 v27, vcc, 0, v27, vcc
	v_add_co_u32_e32 v26, vcc, 0x20000, v26
	s_nop 1
	v_addc_co_u32_e32 v27, vcc, 0, v27, vcc
	global_load_dwordx4 v[56:59], v[26:27], off
.LBB0_1087:
	v_add_co_u32_e32 v24, vcc, 0x22000, v22
	s_nop 1
	v_addc_co_u32_e32 v25, vcc, 0, v23, vcc
	global_load_dwordx4 v[76:79], v[24:25], off
	s_and_b64 vcc, exec, s[56:57]
	s_cbranch_vccnz .LBB0_1089
	v_add_co_u32_e32 v24, vcc, 0x1022000, v22
	s_nop 1
	v_addc_co_u32_e32 v25, vcc, 0, v23, vcc
	global_load_dwordx4 v[64:67], v[24:25], off
	global_load_dwordx4 v[68:71], v[26:27], off offset:64
.LBB0_1089:
	v_add_co_u32_e32 v24, vcc, 0x24000, v22
	s_nop 1
	v_addc_co_u32_e32 v25, vcc, 0, v23, vcc
	global_load_dwordx4 v[92:95], v[24:25], off
	s_and_b64 vcc, exec, s[56:57]
	s_cbranch_vccnz .LBB0_1091
	v_add_co_u32_e32 v24, vcc, 0x1024000, v22
	s_nop 1
	v_addc_co_u32_e32 v25, vcc, 0, v23, vcc
	global_load_dwordx4 v[72:75], v[24:25], off
	global_load_dwordx4 v[80:83], v[26:27], off offset:128
.LBB0_1091:
	v_add_co_u32_e32 v24, vcc, 0x26000, v22
	s_nop 1
	v_addc_co_u32_e32 v25, vcc, 0, v23, vcc
	global_load_dwordx4 v[104:107], v[24:25], off
	s_and_b64 vcc, exec, s[56:57]
	s_cbranch_vccnz .LBB0_1093
	v_add_co_u32_e32 v22, vcc, 0x1026000, v22
	s_nop 1
	v_addc_co_u32_e32 v23, vcc, 0, v23, vcc
	v_add_co_u32_e32 v20, vcc, 0x26000, v20
	global_load_dwordx4 v[84:87], v[22:23], off
	s_nop 0
	v_addc_co_u32_e32 v21, vcc, 0, v21, vcc
	global_load_dwordx4 v[88:91], v[26:27], off offset:192

; DI u32x4 pack8(const float (&f)[8]) { u32x4 r; r[0] = pk2(f[0], f[1]); r[1] = pk2(f[2], f[3]); r[2] = pk2(f[4], f[5]); r[3] = pk2(f[6], f[7]); return r; }
; DI void ssd_scan_phase(bf16_t* P, const bf16_t* BT, const bf16_t* Cc, const bf16_t* CB, const float* dt, const float* acs,
;                        const float* cw, const float* cb, const float* Dp, char* lds, bool dry, int mode, float* Sbuf) {
;     ...
;         const f32x4 a0 = *(const f32x4*)(cAcs + cch * 8), a1 = *(const f32x4*)(cAcs + cch * 8 + 4);
;         const float L2E = 1.44269504f;
;         const float as[8] = {a0[0] * L2E, a0[1] * L2E, a0[2] * L2E, a0[3] * L2E, a1[0] * L2E, a1[1] * L2E, a1[2] * L2E, a1[3] * L2E};
; #pragma unroll
;         for (int j = 0; j < 4; ++j) {
;           const int r = r0 + 32 * j;
;           *(u32x4*)(sBT + swz128(r, cch)) = rB[j];
;           if (mode == 0) {
;             *(u32x4*)(sC + swz128(r, cch)) = rC[j];
;             float f[8]; unpack8(rCB[j], f);
;             const float el = cAcs[r] * L2E;
;             const int lim = r - cch * 8;
; #pragma unroll
;             for (int e = 0; e < 8; ++e) f[e] = (e <= lim) ? f[e] * __builtin_amdgcn_exp2f(el - as[e]) : 0.f;
;             *(u32x4*)(sCBL + swz128(r, cch)) = pack8(f);
.Ls1n:
	v_bitop3_b32 v30, v29, v34, 15 bitop3:0x6c
	v_lshlrev_b32_e32 v30, 4, v30
	v_lshl_add_u32 v33, v29, 8, v30
	v_add_u32_e32 v31, 0x10000, v33
	v_lshrrev_b32_e32 v20, 2, v200
	v_sub_u32_e32 v20, 0x7f, v20
	v_and_b32_e32 v21, 3, v200
	v_lshl_add_u32 v22, v20, 2, s88
	ds_read_b32 v48, v22
	v_lshl_add_u32 v23, v21, 5, s88
	v_lshlrev_b32_e32 v24, 8, v20
	v_and_b32_e32 v25, 15, v20
	v_lshlrev_b32_e32 v26, 3, v21
	v_sub_u32_e32 v26, v20, v26
	v_readfirstlane_b32 s78, v200
	s_lshr_b32 s78, s78, 6
	s_cmp_lg_u64 s[42:43], 0
	s_cbranch_scc1 .Ls1n_w47_0
	s_waitcnt vmcnt(17)
	s_branch .Ls1n_wd_0

; DI u32x4 pack8(const float (&f)[8]) { u32x4 r; r[0] = pk2(f[0], f[1]); r[1] = pk2(f[2], f[3]); r[2] = pk2(f[4], f[5]); r[3] = pk2(f[6], f[7]); return r; }
; DI void ssd_scan_phase(bf16_t* P, const bf16_t* BT, const bf16_t* Cc, const bf16_t* CB, const float* dt, const float* acs,
;                        const float* cw, const float* cb, const float* Dp, char* lds, bool dry, int mode, float* Sbuf) {
;     ...
;         for (int j = 0; j < 4; ++j) {
;           const int r = r0 + 32 * j;
;           *(u32x4*)(sBT + swz128(r, cch)) = rB[j];
;           if (mode == 0) {
;             *(u32x4*)(sC + swz128(r, cch)) = rC[j];
;             float f[8]; unpack8(rCB[j], f);
;             const float el = cAcs[r] * L2E;
;             const int lim = r - cch * 8;
; #pragma unroll
;             for (int e = 0; e < 8; ++e) f[e] = (e <= lim) ? f[e] * __builtin_amdgcn_exp2f(el - as[e]) : 0.f;
;             *(u32x4*)(sCBL + swz128(r, cch)) = pack8(f);
;           }
.Ls1n_wd_0:
	ds_write_b128 v31, v[60:63]
	ds_write_b128 v33, v[52:55] offset:32768
	s_add_i32 s79, s78, 0
	s_cmp_gt_i32 s79, 7
	s_cbranch_scc1 .Ls1n_skip_0
	ds_read_b128 v[36:39], v23
	ds_read_b128 v[42:45], v23 offset:16
	s_waitcnt lgkmcnt(0)
	v_mul_f32_e32 v36, 0x3fb8aa3b, v36
	v_mul_f32_e32 v37, 0x3fb8aa3b, v37
	v_mul_f32_e32 v38, 0x3fb8aa3b, v38
	v_mul_f32_e32 v39, 0x3fb8aa3b, v39
	v_mul_f32_e32 v42, 0x3fb8aa3b, v42
	v_mul_f32_e32 v43, 0x3fb8aa3b, v43
	v_mul_f32_e32 v44, 0x3fb8aa3b, v44
	v_mul_f32_e32 v45, 0x3fb8aa3b, v45
	v_fma_f32 v36, v48, s29, -v36
	v_fma_f32 v37, v48, s29, -v37
	v_fma_f32 v38, v48, s29, -v38
	v_fma_f32 v39, v48, s29, -v39
	v_fma_f32 v42, v48, s29, -v42
	v_fma_f32 v43, v48, s29, -v43
	v_fma_f32 v44, v48, s29, -v44
	v_fma_f32 v45, v48, s29, -v45
	v_exp_f32_e32 v36, v36
	v_exp_f32_e32 v37, v37
	v_exp_f32_e32 v38, v38
	v_exp_f32_e32 v39, v39
	v_exp_f32_e32 v42, v42
	v_exp_f32_e32 v43, v43
	v_exp_f32_e32 v44, v44
	v_exp_f32_e32 v45, v45
	v_lshlrev_b32_e32 v46, 16, v56
	v_and_b32_e32 v47, 0xffff0000, v56
	v_pk_mul_f32 v[36:37], v[36:37], v[46:47]
	v_lshlrev_b32_e32 v46, 16, v57
	v_and_b32_e32 v47, 0xffff0000, v57
	v_pk_mul_f32 v[38:39], v[38:39], v[46:47]
	v_lshlrev_b32_e32 v46, 16, v58
	v_and_b32_e32 v47, 0xffff0000, v58
	v_pk_mul_f32 v[42:43], v[42:43], v[46:47]
	v_lshlrev_b32_e32 v46, 16, v59
	v_and_b32_e32 v47, 0xffff0000, v59
	v_pk_mul_f32 v[44:45], v[44:45], v[46:47]
	s_cmp_lt_i32 s79, 6
	s_cbranch_scc1 .Ls1n_nomask_0
	v_mov_b32_e32 v27, v26
	v_cmp_le_i32_e32 vcc, 0, v27
	s_nop 1
	v_cndmask_b32_e32 v36, 0, v36, vcc
	v_cmp_le_i32_e32 vcc, 1, v27
	s_nop 1
	v_cndmask_b32_e32 v37, 0, v37, vcc
	v_cmp_le_i32_e32 vcc, 2, v27
	s_nop 1
	v_cndmask_b32_e32 v38, 0, v38, vcc
	v_cmp_le_i32_e32 vcc, 3, v27
	s_nop 1
	v_cndmask_b32_e32 v39, 0, v39, vcc
	v_cmp_le_i32_e32 vcc, 4, v27
	s_nop 1
	v_cndmask_b32_e32 v42, 0, v42, vcc
	v_cmp_le_i32_e32 vcc, 5, v27
	s_nop 1
	v_cndmask_b32_e32 v43, 0, v43, vcc
	v_cmp_le_i32_e32 vcc, 6, v27
	s_nop 1
	v_cndmask_b32_e32 v44, 0, v44, vcc
	v_cmp_le_i32_e32 vcc, 7, v27
	s_nop 1
	v_cndmask_b32_e32 v45, 0, v45, vcc
.Ls1n_nomask_0:
	v_cvt_pk_bf16_f32 v36, v36, v37
	v_cvt_pk_bf16_f32 v37, v38, v39
	v_cvt_pk_bf16_f32 v38, v42, v43
	v_cvt_pk_bf16_f32 v39, v44, v45
	v_mov_b32_e32 v22, v21
	v_xor_b32_e32 v22, v22, v25
	v_lshl_add_u32 v22, v22, 4, v24
	ds_write_b128 v22, v[36:39]
.Ls1n_skip_0:
	s_cmp_lg_u64 s[42:43], 0
	s_cbranch_scc1 .Ls1n_w47_1
	s_waitcnt vmcnt(14)
	s_branch .Ls1n_wd_1

; DI u32x4 pack8(const float (&f)[8]) { u32x4 r; r[0] = pk2(f[0], f[1]); r[1] = pk2(f[2], f[3]); r[2] = pk2(f[4], f[5]); r[3] = pk2(f[6], f[7]); return r; }
; DI void ssd_scan_phase(bf16_t* P, const bf16_t* BT, const bf16_t* Cc, const bf16_t* CB, const float* dt, const float* acs,
;                        const float* cw, const float* cb, const float* Dp, char* lds, bool dry, int mode, float* Sbuf) {
;     ...
;         for (int j = 0; j < 4; ++j) {
;           const int r = r0 + 32 * j;
;           *(u32x4*)(sBT + swz128(r, cch)) = rB[j];
;           if (mode == 0) {
;             *(u32x4*)(sC + swz128(r, cch)) = rC[j];
;             float f[8]; unpack8(rCB[j], f);
;             const float el = cAcs[r] * L2E;
;             const int lim = r - cch * 8;
; #pragma unroll
;             for (int e = 0; e < 8; ++e) f[e] = (e <= lim) ? f[e] * __builtin_amdgcn_exp2f(el - as[e]) : 0.f;
;             *(u32x4*)(sCBL + swz128(r, cch)) = pack8(f);
;           }
.Ls1n_wd_1:
	ds_write_b128 v31, v[76:79] offset:8192
	ds_write_b128 v33, v[64:67] offset:40960
	s_add_i32 s79, s78, 2
	s_cmp_gt_i32 s79, 7
	s_cbranch_scc1 .Ls1n_skip_1
	ds_read_b128 v[36:39], v23 offset:128
	ds_read_b128 v[42:45], v23 offset:144
	s_waitcnt lgkmcnt(0)
	v_mul_f32_e32 v36, 0x3fb8aa3b, v36
	v_mul_f32_e32 v37, 0x3fb8aa3b, v37
	v_mul_f32_e32 v38, 0x3fb8aa3b, v38
	v_mul_f32_e32 v39, 0x3fb8aa3b, v39
	v_mul_f32_e32 v42, 0x3fb8aa3b, v42
	v_mul_f32_e32 v43, 0x3fb8aa3b, v43
	v_mul_f32_e32 v44, 0x3fb8aa3b, v44
	v_mul_f32_e32 v45, 0x3fb8aa3b, v45
	v_fma_f32 v36, v48, s29, -v36
	v_fma_f32 v37, v48, s29, -v37
	v_fma_f32 v38, v48, s29, -v38
	v_fma_f32 v39, v48, s29, -v39
	v_fma_f32 v42, v48, s29, -v42
	v_fma_f32 v43, v48, s29, -v43
	v_fma_f32 v44, v48, s29, -v44
	v_fma_f32 v45, v48, s29, -v45
	v_exp_f32_e32 v36, v36
	v_exp_f32_e32 v37, v37
	v_exp_f32_e32 v38, v38
	v_exp_f32_e32 v39, v39
	v_exp_f32_e32 v42, v42
	v_exp_f32_e32 v43, v43
	v_exp_f32_e32 v44, v44
	v_exp_f32_e32 v45, v45
	v_lshlrev_b32_e32 v46, 16, v68
	v_and_b32_e32 v47, 0xffff0000, v68
	v_pk_mul_f32 v[36:37], v[36:37], v[46:47]
	v_lshlrev_b32_e32 v46, 16, v69
	v_and_b32_e32 v47, 0xffff0000, v69
	v_pk_mul_f32 v[38:39], v[38:39], v[46:47]
	v_lshlrev_b32_e32 v46, 16, v70
	v_and_b32_e32 v47, 0xffff0000, v70
	v_pk_mul_f32 v[42:43], v[42:43], v[46:47]
	v_lshlrev_b32_e32 v46, 16, v71
	v_and_b32_e32 v47, 0xffff0000, v71
	v_pk_mul_f32 v[44:45], v[44:45], v[46:47]
	s_cmp_lt_i32 s79, 6
	s_cbranch_scc1 .Ls1n_nomask_1
	v_add_u32_e32 v27, -32, v26
	v_cmp_le_i32_e32 vcc, 0, v27
	s_nop 1
	v_cndmask_b32_e32 v36, 0, v36, vcc
	v_cmp_le_i32_e32 vcc, 1, v27
	s_nop 1
	v_cndmask_b32_e32 v37, 0, v37, vcc
	v_cmp_le_i32_e32 vcc, 2, v27
	s_nop 1
	v_cndmask_b32_e32 v38, 0, v38, vcc
	v_cmp_le_i32_e32 vcc, 3, v27
	s_nop 1
	v_cndmask_b32_e32 v39, 0, v39, vcc
	v_cmp_le_i32_e32 vcc, 4, v27
	s_nop 1
	v_cndmask_b32_e32 v42, 0, v42, vcc
	v_cmp_le_i32_e32 vcc, 5, v27
	s_nop 1
	v_cndmask_b32_e32 v43, 0, v43, vcc
	v_cmp_le_i32_e32 vcc, 6, v27
	s_nop 1
	v_cndmask_b32_e32 v44, 0, v44, vcc
	v_cmp_le_i32_e32 vcc, 7, v27
	s_nop 1
	v_cndmask_b32_e32 v45, 0, v45, vcc
.Ls1n_nomask_1:
	v_cvt_pk_bf16_f32 v36, v36, v37
	v_cvt_pk_bf16_f32 v37, v38, v39
	v_cvt_pk_bf16_f32 v38, v42, v43
	v_cvt_pk_bf16_f32 v39, v44, v45
	v_add_u32_e32 v22, 4, v21
	v_xor_b32_e32 v22, v22, v25
	v_lshl_add_u32 v22, v22, 4, v24
	ds_write_b128 v22, v[36:39]
.Ls1n_skip_1:
	s_cmp_lg_u64 s[42:43], 0
	s_cbranch_scc1 .Ls1n_w47_2
	s_waitcnt vmcnt(11)
	s_branch .Ls1n_wd_2

; DI u32x4 pack8(const float (&f)[8]) { u32x4 r; r[0] = pk2(f[0], f[1]); r[1] = pk2(f[2], f[3]); r[2] = pk2(f[4], f[5]); r[3] = pk2(f[6], f[7]); return r; }
; DI void ssd_scan_phase(bf16_t* P, const bf16_t* BT, const bf16_t* Cc, const bf16_t* CB, const float* dt, const float* acs,
;                        const float* cw, const float* cb, const float* Dp, char* lds, bool dry, int mode, float* Sbuf) {
;     ...
;         for (int j = 0; j < 4; ++j) {
;           const int r = r0 + 32 * j;
;           *(u32x4*)(sBT + swz128(r, cch)) = rB[j];
;           if (mode == 0) {
;             *(u32x4*)(sC + swz128(r, cch)) = rC[j];
;             float f[8]; unpack8(rCB[j], f);
;             const float el = cAcs[r] * L2E;
;             const int lim = r - cch * 8;
; #pragma unroll
;             for (int e = 0; e < 8; ++e) f[e] = (e <= lim) ? f[e] * __builtin_amdgcn_exp2f(el - as[e]) : 0.f;
;             *(u32x4*)(sCBL + swz128(r, cch)) = pack8(f);
;           }
.Ls1n_wd_2:
	ds_write_b128 v31, v[92:95] offset:16384
	ds_write_b128 v33, v[72:75] offset:49152
	s_add_i32 s79, s78, 4
	s_cmp_gt_i32 s79, 7
	s_cbranch_scc1 .Ls1n_skip_2
	ds_read_b128 v[36:39], v23 offset:256
	ds_read_b128 v[42:45], v23 offset:272
	s_waitcnt lgkmcnt(0)
	v_mul_f32_e32 v36, 0x3fb8aa3b, v36
	v_mul_f32_e32 v37, 0x3fb8aa3b, v37
	v_mul_f32_e32 v38, 0x3fb8aa3b, v38
	v_mul_f32_e32 v39, 0x3fb8aa3b, v39
	v_mul_f32_e32 v42, 0x3fb8aa3b, v42
	v_mul_f32_e32 v43, 0x3fb8aa3b, v43
	v_mul_f32_e32 v44, 0x3fb8aa3b, v44
	v_mul_f32_e32 v45, 0x3fb8aa3b, v45
	v_fma_f32 v36, v48, s29, -v36
	v_fma_f32 v37, v48, s29, -v37
	v_fma_f32 v38, v48, s29, -v38
	v_fma_f32 v39, v48, s29, -v39
	v_fma_f32 v42, v48, s29, -v42
	v_fma_f32 v43, v48, s29, -v43
	v_fma_f32 v44, v48, s29, -v44
	v_fma_f32 v45, v48, s29, -v45
	v_exp_f32_e32 v36, v36
	v_exp_f32_e32 v37, v37
	v_exp_f32_e32 v38, v38
	v_exp_f32_e32 v39, v39
	v_exp_f32_e32 v42, v42
	v_exp_f32_e32 v43, v43
	v_exp_f32_e32 v44, v44
	v_exp_f32_e32 v45, v45
	v_lshlrev_b32_e32 v46, 16, v80
	v_and_b32_e32 v47, 0xffff0000, v80
	v_pk_mul_f32 v[36:37], v[36:37], v[46:47]
	v_lshlrev_b32_e32 v46, 16, v81
	v_and_b32_e32 v47, 0xffff0000, v81
	v_pk_mul_f32 v[38:39], v[38:39], v[46:47]
	v_lshlrev_b32_e32 v46, 16, v82
	v_and_b32_e32 v47, 0xffff0000, v82
	v_pk_mul_f32 v[42:43], v[42:43], v[46:47]
	v_lshlrev_b32_e32 v46, 16, v83
	v_and_b32_e32 v47, 0xffff0000, v83
	v_pk_mul_f32 v[44:45], v[44:45], v[46:47]
	s_cmp_lt_i32 s79, 6
	s_cbranch_scc1 .Ls1n_nomask_2
	v_add_u32_e32 v27, -64, v26
	v_cmp_le_i32_e32 vcc, 0, v27
	s_nop 1
	v_cndmask_b32_e32 v36, 0, v36, vcc
	v_cmp_le_i32_e32 vcc, 1, v27
	s_nop 1
	v_cndmask_b32_e32 v37, 0, v37, vcc
	v_cmp_le_i32_e32 vcc, 2, v27
	s_nop 1
	v_cndmask_b32_e32 v38, 0, v38, vcc
	v_cmp_le_i32_e32 vcc, 3, v27
	s_nop 1
	v_cndmask_b32_e32 v39, 0, v39, vcc
	v_cmp_le_i32_e32 vcc, 4, v27
	s_nop 1
	v_cndmask_b32_e32 v42, 0, v42, vcc
	v_cmp_le_i32_e32 vcc, 5, v27
	s_nop 1
	v_cndmask_b32_e32 v43, 0, v43, vcc
	v_cmp_le_i32_e32 vcc, 6, v27
	s_nop 1
	v_cndmask_b32_e32 v44, 0, v44, vcc
	v_cmp_le_i32_e32 vcc, 7, v27
	s_nop 1
	v_cndmask_b32_e32 v45, 0, v45, vcc
.Ls1n_nomask_2:
	v_cvt_pk_bf16_f32 v36, v36, v37
	v_cvt_pk_bf16_f32 v37, v38, v39
	v_cvt_pk_bf16_f32 v38, v42, v43
	v_cvt_pk_bf16_f32 v39, v44, v45
	v_add_u32_e32 v22, 8, v21
	v_xor_b32_e32 v22, v22, v25
	v_lshl_add_u32 v22, v22, 4, v24
	ds_write_b128 v22, v[36:39]
.Ls1n_skip_2:
	s_cmp_lg_u64 s[42:43], 0
	s_cbranch_scc1 .Ls1n_w47_3
	s_waitcnt vmcnt(8)
	s_branch .Ls1n_wd_3

; DI u32x4 pack8(const float (&f)[8]) { u32x4 r; r[0] = pk2(f[0], f[1]); r[1] = pk2(f[2], f[3]); r[2] = pk2(f[4], f[5]); r[3] = pk2(f[6], f[7]); return r; }
; DI void ssd_scan_phase(bf16_t* P, const bf16_t* BT, const bf16_t* Cc, const bf16_t* CB, const float* dt, const float* acs,
;                        const float* cw, const float* cb, const float* Dp, char* lds, bool dry, int mode, float* Sbuf) {
;     ...
;         for (int j = 0; j < 4; ++j) {
;           const int r = r0 + 32 * j;
;           *(u32x4*)(sBT + swz128(r, cch)) = rB[j];
;           if (mode == 0) {
;             *(u32x4*)(sC + swz128(r, cch)) = rC[j];
;             float f[8]; unpack8(rCB[j], f);
;             const float el = cAcs[r] * L2E;
;             const int lim = r - cch * 8;
; #pragma unroll
;             for (int e = 0; e < 8; ++e) f[e] = (e <= lim) ? f[e] * __builtin_amdgcn_exp2f(el - as[e]) : 0.f;
;             *(u32x4*)(sCBL + swz128(r, cch)) = pack8(f);
;           }
.Ls1n_wd_3:
	ds_write_b128 v31, v[104:107] offset:24576
	ds_write_b128 v33, v[84:87] offset:57344
	s_add_i32 s79, s78, 6
	s_cmp_gt_i32 s79, 7
	s_cbranch_scc1 .Ls1n_skip_3
	ds_read_b128 v[36:39], v23 offset:384
	ds_read_b128 v[42:45], v23 offset:400
	s_waitcnt lgkmcnt(0)
	v_mul_f32_e32 v36, 0x3fb8aa3b, v36
	v_mul_f32_e32 v37, 0x3fb8aa3b, v37
	v_mul_f32_e32 v38, 0x3fb8aa3b, v38
	v_mul_f32_e32 v39, 0x3fb8aa3b, v39
	v_mul_f32_e32 v42, 0x3fb8aa3b, v42
	v_mul_f32_e32 v43, 0x3fb8aa3b, v43
	v_mul_f32_e32 v44, 0x3fb8aa3b, v44
	v_mul_f32_e32 v45, 0x3fb8aa3b, v45
	v_fma_f32 v36, v48, s29, -v36
	v_fma_f32 v37, v48, s29, -v37
	v_fma_f32 v38, v48, s29, -v38
	v_fma_f32 v39, v48, s29, -v39
	v_fma_f32 v42, v48, s29, -v42
	v_fma_f32 v43, v48, s29, -v43
	v_fma_f32 v44, v48, s29, -v44
	v_fma_f32 v45, v48, s29, -v45
	v_exp_f32_e32 v36, v36
	v_exp_f32_e32 v37, v37
	v_exp_f32_e32 v38, v38
	v_exp_f32_e32 v39, v39
	v_exp_f32_e32 v42, v42
	v_exp_f32_e32 v43, v43
	v_exp_f32_e32 v44, v44
	v_exp_f32_e32 v45, v45
	v_lshlrev_b32_e32 v46, 16, v88
	v_and_b32_e32 v47, 0xffff0000, v88
	v_pk_mul_f32 v[36:37], v[36:37], v[46:47]
	v_lshlrev_b32_e32 v46, 16, v89
	v_and_b32_e32 v47, 0xffff0000, v89
	v_pk_mul_f32 v[38:39], v[38:39], v[46:47]
	v_lshlrev_b32_e32 v46, 16, v90
	v_and_b32_e32 v47, 0xffff0000, v90
	v_pk_mul_f32 v[42:43], v[42:43], v[46:47]
	v_lshlrev_b32_e32 v46, 16, v91
	v_and_b32_e32 v47, 0xffff0000, v91
	v_pk_mul_f32 v[44:45], v[44:45], v[46:47]
	s_cmp_lt_i32 s79, 6
	s_cbranch_scc1 .Ls1n_nomask_3
	v_add_u32_e32 v27, -96, v26
	v_cmp_le_i32_e32 vcc, 0, v27
	s_nop 1
	v_cndmask_b32_e32 v36, 0, v36, vcc
	v_cmp_le_i32_e32 vcc, 1, v27
	s_nop 1
	v_cndmask_b32_e32 v37, 0, v37, vcc
	v_cmp_le_i32_e32 vcc, 2, v27
	s_nop 1
	v_cndmask_b32_e32 v38, 0, v38, vcc
	v_cmp_le_i32_e32 vcc, 3, v27
	s_nop 1
	v_cndmask_b32_e32 v39, 0, v39, vcc
	v_cmp_le_i32_e32 vcc, 4, v27
	s_nop 1
	v_cndmask_b32_e32 v42, 0, v42, vcc
	v_cmp_le_i32_e32 vcc, 5, v27
	s_nop 1
	v_cndmask_b32_e32 v43, 0, v43, vcc
	v_cmp_le_i32_e32 vcc, 6, v27
	s_nop 1
	v_cndmask_b32_e32 v44, 0, v44, vcc
	v_cmp_le_i32_e32 vcc, 7, v27
	s_nop 1
	v_cndmask_b32_e32 v45, 0, v45, vcc
.Ls1n_nomask_3:
	v_cvt_pk_bf16_f32 v36, v36, v37
	v_cvt_pk_bf16_f32 v37, v38, v39
	v_cvt_pk_bf16_f32 v38, v42, v43
	v_cvt_pk_bf16_f32 v39, v44, v45
	v_add_u32_e32 v22, 12, v21
	v_xor_b32_e32 v22, v22, v25
	v_lshl_add_u32 v22, v22, 4, v24
	ds_write_b128 v22, v[36:39]
.Ls1n_skip_3:
	s_branch .LBB0_1060
.LBB0_1115:
	global_load_dwordx4 v[96:99], v[20:21], off
	s_or_b64 exec, exec, s[80:81]
	s_and_saveexec_b64 s[80:81], s[42:43]
	s_cbranch_execz .LBB0_1095
